# pass-1 SSD unit: the At/DTt loads + ds_bpermute prefix-scan prologue moved behind the issue of the unit's 34 main input loads (registers renamed), overlapping the two load round trips
# baseline (speedup 1.0000x reference)
; #define LAS __attribute__((address_space(3)))
; __device__ __forceinline__ float bperm(float v, int srclane) { return __builtin_bit_cast(float, __builtin_amdgcn_ds_bpermute(srclane << 2, __builtin_bit_cast(int, v))); }
; template <int PASS>
; __device__ __forceinline__ void ssd_unit(LAS unsigned char* lds, int ch, int g, const bf16* PROJ, const bf16* XBC, const float* At, const float* DTt, bf16* STS, float* DECS, bf16* OMIX,
;                                          const float* d_skip, const float* ssd_norm) {
;     ...
;         const int d = wave >> 2, hl = wave & 3; const size_t ix = ((size_t)d * MALL + m0 + lane) * 8 + 4 * g + hl;
;         float v = At[ix]; const float dt = DTt[ix];
; #pragma unroll
;         for (int o = 1; o < 64; o <<= 1) { const float t = bperm(v, d ? lane + o : lane - o); if (d ? (lane + o < 64) : (lane >= o)) v += t; }
;     ...
;             for (int i2 = 0; i2 < 2; ++i2) { const int idx = tid + NT * i2, tok = idx >> 4, c8 = (idx & 15) * 8;
;                 const v4u u = *(const v4u*)(XBC + (m0 + tok) * 768 + 512 + ((c8 < 64) ? 64 * g + c8 : 128 + 64 * g + (c8 - 64)));
;                 *(LAS v4u*)(((c8 < 64) ? BM : CM) + tok * RS + (c8 & 63) * 2) = u; }
;             const int p = tid & 63, hl = (tid >> 6) & 3, half = tid >> 8; const bf16* xp = XBC + (m0 + 32 * half) * 768 + (4 * g + hl) * 64 + p; unsigned xv[32];
; #pragma unroll
;             for (int jj = 0; jj < 32; ++jj) xv[jj] = xp[(size_t)jj * 768];
.LBB0_789:
	v_mov_b32_e32 v82, v0
	s_ashr_i32 s8, s63, 1
	s_waitcnt vmcnt(2)
	v_ashrrev_i32_e32 v2, 6, v82
	s_ashr_i32 s9, s8, 31
	v_readfirstlane_b32 s64, v2
	s_lshl_b64 s[6:7], s[8:9], 6
	v_and_b32_e32 v119, 63, v82
	v_lshlrev_b32_e32 v123, 2, v119
	v_ashrrev_i32_e32 v10, 4, v82
	v_ashrrev_i32_e32 v11, 31, v10
	v_lshlrev_b32_e32 v6, 3, v82
	v_lshl_add_u64 v[2:3], s[6:7], 0, v[10:11]
	v_mad_u64_u32 v[4:5], s[0:1], v2, s42, v[112:113]
	v_and_b32_e32 v2, 64, v6
	v_and_b32_e32 v22, 0x78, v6
	v_add_u32_e32 v2, s34, v2
	v_mad_i32_i24 v5, v3, s42, v5
	v_add_lshl_u32 v110, v2, v22, 1
	v_lshl_add_u64 v[2:3], v[4:5], 0, v[110:111]
	v_add_u32_e32 v4, 0x200, v82
	v_ashrrev_i32_e32 v12, 4, v4
	v_ashrrev_i32_e32 v84, 8, v82
	v_ashrrev_i32_e32 v13, 31, v12
	v_lshlrev_b32_e32 v14, 5, v84
	v_lshl_add_u64 v[4:5], s[6:7], 0, v[12:13]
	v_ashrrev_i32_e32 v15, 31, v14
	v_mad_u64_u32 v[6:7], s[0:1], v4, s42, v[112:113]
	v_bfe_u32 v83, v82, 6, 2
	v_lshl_add_u64 v[14:15], s[6:7], 0, v[14:15]
	v_mad_i32_i24 v7, v5, s42, v7
	v_mad_u64_u32 v[16:17], s[0:1], v14, s42, v[112:113]
	v_or_b32_e32 v11, s31, v83
	v_lshl_add_u64 v[6:7], v[6:7], 0, v[110:111]
	v_mad_i32_i24 v17, v15, s42, v17
	v_lshlrev_b32_e32 v110, 7, v11
	v_lshl_add_u64 v[14:15], v[16:17], 0, v[110:111]
	v_lshlrev_b32_e32 v110, 1, v119
	v_lshl_add_u64 v[14:15], v[14:15], 0, v[110:111]
	v_add_co_u32_e32 v16, vcc, s44, v14
	global_load_dwordx4 v[2:5], v[2:3], off offset:1024
	s_nop 0
	global_load_dwordx4 v[6:9], v[6:7], off offset:1024
	v_addc_co_u32_e32 v17, vcc, 0, v15, vcc
	v_add_co_u32_e32 v18, vcc, s45, v14
	v_lshlrev_b32_e32 v11, 4, v82
	s_nop 0
	v_addc_co_u32_e32 v19, vcc, 0, v15, vcc
	global_load_ushort v85, v[14:15], off
	global_load_ushort v86, v[14:15], off offset:1536
	global_load_ushort v87, v[14:15], off offset:3072
	global_load_ushort v88, v[16:17], off offset:512
	global_load_ushort v89, v[16:17], off offset:2048
	global_load_ushort v90, v[16:17], off offset:3584
	global_load_ushort v91, v[18:19], off offset:1024
	global_load_ushort v92, v[18:19], off offset:2560
	v_add_co_u32_e32 v16, vcc, s46, v14
	v_and_b32_e32 v11, 0x70, v11
	s_nop 0
	v_addc_co_u32_e32 v17, vcc, 0, v15, vcc
	v_add_co_u32_e32 v18, vcc, s47, v14
	v_mul_lo_u32 v10, v10, s43
	s_nop 0
	v_addc_co_u32_e32 v19, vcc, 0, v15, vcc
	v_add_co_u32_e32 v20, vcc, s50, v14
	s_ashr_i32 s13, s64, 1
	s_nop 0
	v_addc_co_u32_e32 v21, vcc, 0, v15, vcc
	global_load_ushort v93, v[16:17], off
	global_load_ushort v94, v[16:17], off offset:1536
	global_load_ushort v95, v[16:17], off offset:3072
	global_load_ushort v96, v[18:19], off offset:512
	global_load_ushort v97, v[18:19], off offset:2048
	global_load_ushort v98, v[18:19], off offset:3584
	global_load_ushort v99, v[20:21], off offset:1024
	global_load_ushort v100, v[20:21], off offset:2560
	v_add_co_u32_e32 v16, vcc, s51, v14
	s_add_i32 s0, s13, s31
	s_nop 0
	v_addc_co_u32_e32 v17, vcc, 0, v15, vcc
	v_add_co_u32_e32 v18, vcc, s52, v14
	s_lshl_b32 s1, s8, 4
	s_nop 0
	v_addc_co_u32_e32 v19, vcc, 0, v15, vcc
	v_add_co_u32_e32 v20, vcc, s53, v14
	s_lshl_b32 s3, s0, 1
	s_nop 0
	v_addc_co_u32_e32 v21, vcc, 0, v15, vcc
	global_load_ushort v101, v[16:17], off
	global_load_ushort v102, v[16:17], off offset:1536
	global_load_ushort v103, v[16:17], off offset:3072
	global_load_ushort v104, v[18:19], off offset:512
	global_load_ushort v105, v[18:19], off offset:2048
	global_load_ushort v106, v[18:19], off offset:3584
	global_load_ushort v107, v[20:21], off offset:1024
	global_load_ushort v108, v[20:21], off offset:2560
	v_add_co_u32_e32 v16, vcc, s54, v14
	s_add_i32 s4, s3, s1
	s_nop 0
	v_addc_co_u32_e32 v17, vcc, 0, v15, vcc
	v_add_co_u32_e32 v18, vcc, s55, v14
	s_ashr_i32 s5, s4, 31
	s_nop 0
	v_addc_co_u32_e32 v19, vcc, 0, v15, vcc
	v_add_co_u32_e32 v14, vcc, s56, v14
	v_and_b32_e32 v140, 15, v82
	s_nop 0
	v_addc_co_u32_e32 v15, vcc, 0, v15, vcc
	global_load_ushort v109, v[16:17], off
	global_load_ushort v121, v[16:17], off offset:1536
	global_load_ushort v144, v[16:17], off offset:3072
	global_load_ushort v145, v[18:19], off offset:512
	global_load_ushort v146, v[18:19], off offset:2048
	global_load_ushort v147, v[18:19], off offset:3584
	global_load_ushort v148, v[14:15], off offset:1024
	global_load_ushort v149, v[14:15], off offset:2560
	s_ashr_i32 s66, s64, 2
	s_mul_hi_i32 s67, s66, 0x4400
	s_mulk_i32 s66, 0x4400
	s_add_u32 s66, s66, s6
	s_addc_u32 s67, s67, s7
	v_or_b32_e32 v164, s66, v119
	v_mov_b32_e32 v165, s67
	v_lshlrev_b64 v[164:165], 3, v[164:165]
	v_or_b32_e32 v164, s31, v164
	v_and_or_b32 v164, s64, 3, v164
	v_lshlrev_b64 v[166:167], 2, v[164:165]
	v_lshl_add_u64 v[164:165], s[22:23], 0, v[166:167]
	global_load_dword v164, v[164:165], off
	v_lshl_add_u64 v[166:167], s[14:15], 0, v[166:167]
	global_load_dword v165, v[166:167], off
	s_cmp_gt_u32 s64, 3
	s_cselect_b64 s[66:67], -1, 0
	s_cmp_lt_u32 s64, 4
	s_cselect_b64 s[36:37], -1, 0
	s_and_b64 vcc, s[36:37], exec
	s_cselect_b32 s68, -1, 1
	v_add_lshl_u32 v166, s68, v119, 2
	s_waitcnt vmcnt(1)
	ds_bpermute_b32 v166, v166, v164
	s_cbranch_vccnz .LBB0_791
	v_cmp_ne_u32_e32 vcc, 63, v119
	s_and_b64 s[70:71], vcc, exec
	s_cbranch_execz .LBB0_792
	s_branch .LBB0_793
.LBB0_791:
	s_mov_b64 s[70:71], 0
.LBB0_792:
	v_cmp_ne_u32_e32 vcc, 0, v119
	s_andn2_b64 s[70:71], s[70:71], exec
	s_and_b64 s[72:73], vcc, exec
	s_or_b64 s[70:71], s[70:71], s[72:73]
.LBB0_793:
	s_and_saveexec_b64 s[72:73], s[70:71]
	s_cbranch_execz .LBB0_795
	s_waitcnt lgkmcnt(0)
	v_add_f32_e32 v164, v164, v166
.LBB0_795:
	s_or_b64 exec, exec, s[72:73]
	s_and_b64 s[70:71], s[36:37], exec
	s_cselect_b32 s68, -2, 2
	s_waitcnt lgkmcnt(0)
	v_add_lshl_u32 v166, s68, v119, 2
	ds_bpermute_b32 v166, v166, v164
	v_cndmask_b32_e64 v167, 0, 1, s[66:67]
	v_cmp_ne_u32_e64 s[70:71], 1, v167
	s_andn2_b64 vcc, exec, s[66:67]
	s_cbranch_vccnz .LBB0_797
	v_cmp_gt_u32_e32 vcc, 62, v119
	s_and_b64 s[66:67], vcc, exec
	s_cbranch_execz .LBB0_798
	s_branch .LBB0_799
.LBB0_797:
	s_mov_b64 s[66:67], 0
.LBB0_798:
	v_cmp_lt_u32_e32 vcc, 1, v119
	s_andn2_b64 s[66:67], s[66:67], exec
	s_and_b64 s[72:73], vcc, exec
	s_or_b64 s[66:67], s[66:67], s[72:73]
.LBB0_799:
	s_and_saveexec_b64 s[72:73], s[66:67]
	s_cbranch_execz .LBB0_801
	s_waitcnt lgkmcnt(0)
	v_add_f32_e32 v164, v164, v166
.LBB0_801:
	s_or_b64 exec, exec, s[72:73]
	s_and_b64 s[66:67], s[36:37], exec
	s_cselect_b32 s66, -4, 4
	s_waitcnt lgkmcnt(0)
	v_add_lshl_u32 v166, s66, v119, 2
	ds_bpermute_b32 v166, v166, v164
	s_and_b64 vcc, exec, s[70:71]
	s_cbranch_vccnz .LBB0_803
	v_cmp_gt_u32_e32 vcc, 60, v119
	s_and_b64 s[66:67], vcc, exec
	s_cbranch_execz .LBB0_804
	s_branch .LBB0_805

; __device__ __forceinline__ float bperm(float v, int srclane) { return __builtin_bit_cast(float, __builtin_amdgcn_ds_bpermute(srclane << 2, __builtin_bit_cast(int, v))); }
; template <int PASS>
; __device__ __forceinline__ void ssd_unit(LAS unsigned char* lds, int ch, int g, const bf16* PROJ, const bf16* XBC, const float* At, const float* DTt, bf16* STS, float* DECS, bf16* OMIX,
;                                          const float* d_skip, const float* ssd_norm) {
;     ...
;         for (int o = 1; o < 64; o <<= 1) { const float t = bperm(v, d ? lane + o : lane - o); if (d ? (lane + o < 64) : (lane >= o)) v += t; }
.LBB0_804:
	v_cmp_lt_u32_e32 vcc, 3, v119
	s_andn2_b64 s[66:67], s[66:67], exec
	s_and_b64 s[72:73], vcc, exec
	s_or_b64 s[66:67], s[66:67], s[72:73]

; __device__ __forceinline__ float bperm(float v, int srclane) { return __builtin_bit_cast(float, __builtin_amdgcn_ds_bpermute(srclane << 2, __builtin_bit_cast(int, v))); }
; template <int PASS>
; __device__ __forceinline__ void ssd_unit(LAS unsigned char* lds, int ch, int g, const bf16* PROJ, const bf16* XBC, const float* At, const float* DTt, bf16* STS, float* DECS, bf16* OMIX,
;                                          const float* d_skip, const float* ssd_norm) {
;     ...
;         for (int o = 1; o < 64; o <<= 1) { const float t = bperm(v, d ? lane + o : lane - o); if (d ? (lane + o < 64) : (lane >= o)) v += t; }
.LBB0_807:
	s_or_b64 exec, exec, s[72:73]
	s_and_b64 s[66:67], s[36:37], exec
	s_cselect_b32 s66, -8, 8
	s_waitcnt lgkmcnt(0)
	v_add_lshl_u32 v166, s66, v119, 2
	ds_bpermute_b32 v166, v166, v164
	s_and_b64 vcc, exec, s[70:71]
	s_cbranch_vccnz .LBB0_809
	v_cmp_gt_u32_e32 vcc, 56, v119
	s_and_b64 s[66:67], vcc, exec
	s_cbranch_execz .LBB0_810
	s_branch .LBB0_811

; __device__ __forceinline__ float bperm(float v, int srclane) { return __builtin_bit_cast(float, __builtin_amdgcn_ds_bpermute(srclane << 2, __builtin_bit_cast(int, v))); }
; template <int PASS>
; __device__ __forceinline__ void ssd_unit(LAS unsigned char* lds, int ch, int g, const bf16* PROJ, const bf16* XBC, const float* At, const float* DTt, bf16* STS, float* DECS, bf16* OMIX,
;                                          const float* d_skip, const float* ssd_norm) {
;     ...
;         for (int o = 1; o < 64; o <<= 1) { const float t = bperm(v, d ? lane + o : lane - o); if (d ? (lane + o < 64) : (lane >= o)) v += t; }
.LBB0_810:
	v_cmp_lt_u32_e32 vcc, 7, v119
	s_andn2_b64 s[66:67], s[66:67], exec
	s_and_b64 s[72:73], vcc, exec
	s_or_b64 s[66:67], s[66:67], s[72:73]

; __device__ __forceinline__ float bperm(float v, int srclane) { return __builtin_bit_cast(float, __builtin_amdgcn_ds_bpermute(srclane << 2, __builtin_bit_cast(int, v))); }
; template <int PASS>
; __device__ __forceinline__ void ssd_unit(LAS unsigned char* lds, int ch, int g, const bf16* PROJ, const bf16* XBC, const float* At, const float* DTt, bf16* STS, float* DECS, bf16* OMIX,
;                                          const float* d_skip, const float* ssd_norm) {
;     ...
;         for (int o = 1; o < 64; o <<= 1) { const float t = bperm(v, d ? lane + o : lane - o); if (d ? (lane + o < 64) : (lane >= o)) v += t; }
.LBB0_813:
	s_or_b64 exec, exec, s[72:73]
	s_and_b64 s[66:67], s[36:37], exec
	s_cselect_b32 s66, -16, 16
	s_waitcnt lgkmcnt(0)
	v_add_lshl_u32 v166, s66, v119, 2
	ds_bpermute_b32 v166, v166, v164
	s_and_b64 vcc, exec, s[70:71]
	s_cbranch_vccnz .LBB0_815
	v_cmp_gt_u32_e32 vcc, 48, v119
	s_and_b64 s[66:67], vcc, exec
	s_cbranch_execz .LBB0_816
	s_branch .LBB0_817

; __device__ __forceinline__ float bperm(float v, int srclane) { return __builtin_bit_cast(float, __builtin_amdgcn_ds_bpermute(srclane << 2, __builtin_bit_cast(int, v))); }
; template <int PASS>
; __device__ __forceinline__ void ssd_unit(LAS unsigned char* lds, int ch, int g, const bf16* PROJ, const bf16* XBC, const float* At, const float* DTt, bf16* STS, float* DECS, bf16* OMIX,
;                                          const float* d_skip, const float* ssd_norm) {
;     ...
;         for (int o = 1; o < 64; o <<= 1) { const float t = bperm(v, d ? lane + o : lane - o); if (d ? (lane + o < 64) : (lane >= o)) v += t; }
.LBB0_816:
	v_cmp_lt_u32_e32 vcc, 15, v119
	s_andn2_b64 s[66:67], s[66:67], exec
	s_and_b64 s[72:73], vcc, exec
	s_or_b64 s[66:67], s[66:67], s[72:73]

; __device__ __forceinline__ float bperm(float v, int srclane) { return __builtin_bit_cast(float, __builtin_amdgcn_ds_bpermute(srclane << 2, __builtin_bit_cast(int, v))); }
; template <int PASS>
; __device__ __forceinline__ void ssd_unit(LAS unsigned char* lds, int ch, int g, const bf16* PROJ, const bf16* XBC, const float* At, const float* DTt, bf16* STS, float* DECS, bf16* OMIX,
;                                          const float* d_skip, const float* ssd_norm) {
;     ...
;         for (int o = 1; o < 64; o <<= 1) { const float t = bperm(v, d ? lane + o : lane - o); if (d ? (lane + o < 64) : (lane >= o)) v += t; }
.LBB0_819:
	s_or_b64 exec, exec, s[72:73]
	s_and_b64 s[66:67], s[36:37], exec
	s_cselect_b32 s66, 0xffffffe0, 32
	s_waitcnt lgkmcnt(0)
	v_add_lshl_u32 v166, s66, v119, 2
	ds_bpermute_b32 v166, v166, v164
	s_and_b64 vcc, exec, s[70:71]
	s_cbranch_vccnz .LBB0_821
	v_cmp_gt_u32_e32 vcc, 32, v119
	s_and_b64 s[66:67], vcc, exec
	s_cbranch_execz .LBB0_822
	s_branch .LBB0_823

; __device__ __forceinline__ float bperm(float v, int srclane) { return __builtin_bit_cast(float, __builtin_amdgcn_ds_bpermute(srclane << 2, __builtin_bit_cast(int, v))); }
; template <int PASS>
; __device__ __forceinline__ void ssd_unit(LAS unsigned char* lds, int ch, int g, const bf16* PROJ, const bf16* XBC, const float* At, const float* DTt, bf16* STS, float* DECS, bf16* OMIX,
;                                          const float* d_skip, const float* ssd_norm) {
;     ...
;         for (int o = 1; o < 64; o <<= 1) { const float t = bperm(v, d ? lane + o : lane - o); if (d ? (lane + o < 64) : (lane >= o)) v += t; }
.LBB0_822:
	v_cmp_lt_u32_e32 vcc, 31, v119
	s_andn2_b64 s[66:67], s[66:67], exec
	s_and_b64 s[70:71], vcc, exec
	s_or_b64 s[66:67], s[66:67], s[70:71]
.LBB0_823:
	s_and_saveexec_b64 s[70:71], s[66:67]
	s_cbranch_execz .LBB0_825
	s_waitcnt lgkmcnt(0)
	v_add_f32_e32 v164, v164, v166
; template <int PASS>
; __device__ __forceinline__ void ssd_unit(LAS unsigned char* lds, int ch, int g, const bf16* PROJ, const bf16* XBC, const float* At, const float* DTt, bf16* STS, float* DECS, bf16* OMIX,
;                                          const float* d_skip, const float* ssd_norm) {
;     ...
;         SC[wave * 64 + lane] = v; DL[wave * 64 + lane] = dt;
;         if (lane == (d ? 0 : 63)) TOT[wave] = v;
;     ...
;             for (int i2 = 0; i2 < 2; ++i2) { const int idx = tid + NT * i2, tok = idx >> 4, c8 = (idx & 15) * 8;
;                 const v4u u = *(const v4u*)(XBC + (m0 + tok) * 768 + 512 + ((c8 < 64) ? 64 * g + c8 : 128 + 64 * g + (c8 - 64)));
;                 *(LAS v4u*)(((c8 < 64) ? BM : CM) + tok * RS + (c8 & 63) * 2) = u; }
;             const int p = tid & 63, hl = (tid >> 6) & 3, half = tid >> 8; const bf16* xp = XBC + (m0 + 32 * half) * 768 + (4 * g + hl) * 64 + p; unsigned xv[32];
; #pragma unroll
;             for (int jj = 0; jj < 32; ++jj) xv[jj] = xp[(size_t)jj * 768];
; #pragma unroll
;             for (int jj = 0; jj < 32; ++jj) asm volatile("" : "+v"(xv[jj]));
;             LAS unsigned char* dst = XT + (hl * 64 + p) * RS + half * 64;
; #pragma unroll
;             for (int o8 = 0; o8 < 4; ++o8) *(LAS v4u*)(dst + o8 * 16) = (v4u){xv[8 * o8] | (xv[8 * o8 + 1] << 16), xv[8 * o8 + 2] | (xv[8 * o8 + 3] << 16), xv[8 * o8 + 4] | (xv[8 * o8 + 5] << 16), xv[8 * o8 + 6] | (xv[8 * o8 + 7] << 16)};
;         }
;         const int hl = wave >> 1, ih = wave & 1, hh = 4 * g + hl;
;         bf16x8 sf[2][4][2];
; #pragma unroll
;         for (int d = 0; d < 2; ++d)
; #pragma unroll
;             for (int pt = 0; pt < 4; ++pt)
; #pragma unroll
;                 for (int ks = 0; ks < 2; ++ks) sf[d][pt][ks] = *(const bf16x8*)(STS + (size_t)((ch * 8 + hh) * 2 + d) * 4096 + (16 * pt + lr) * 64 + 32 * ks + 8 * lq);
;         v2u zz8[2][4];
; #pragma unroll
;         for (int i2 = 0; i2 < 2; ++i2)
; #pragma unroll
;             for (int pt = 0; pt < 4; ++pt) zz8[i2][pt] = *(const v2u*)(PROJ + (m0 + 16 * (2 * ih + i2) + lr) * LDP + PZ + hh * 64 + 16 * pt + 4 * lq);
;         const float ds_e = d_skip[hh];
;         f32x4 gn8[4];
; #pragma unroll
;         for (int pt = 0; pt < 4; ++pt) gn8[pt] = *(const f32x4*)(ssd_norm + 256 * g + 64 * hl + 16 * pt + 4 * lq);
;         __syncthreads();
;         {
;             const int ait = wave >> 1, i = 16 * ait + lr;
.LBB0_825:
	s_or_b64 exec, exec, s[70:71]
	s_waitcnt lgkmcnt(0)
	v_lshl_or_b32 v166, s64, 8, v123
	s_and_b64 s[66:67], s[36:37], exec
	v_add_u32_e32 v166, 0, v166
	s_cselect_b32 s66, 63, 0
	v_add_u32_e32 v167, 0x18c00, v166
	v_add_u32_e32 v166, 0x19400, v166
	v_cmp_eq_u32_e32 vcc, s66, v119
	ds_write_b32 v167, v164
	s_waitcnt vmcnt(0)
	ds_write_b32 v166, v165
	s_and_saveexec_b64 s[66:67], vcc
	s_lshl_b32 s68, s64, 2
	s_add_i32 s68, s68, 0
	s_add_i32 s68, s68, 0x19c00
	v_mov_b32_e32 v165, s68
	ds_write_b32 v165, v164
	s_or_b64 exec, exec, s[66:67]
	v_cmp_gt_u32_e32 vcc, 64, v22
	s_lshl_b64 s[8:9], s[4:5], 13
	s_or_b32 s4, s4, 1
	v_cndmask_b32_e32 v13, 0, v1, vcc
	v_add3_u32 v10, v13, v10, v11
	s_ashr_i32 s5, s4, 31
	s_lshl_b64 s[4:5], s[4:5], 13
	s_and_b32 s12, s64, 1
	s_lshl_b32 s3, s12, 5
	v_or_b32_e32 v143, s3, v140
	v_or_b32_e32 v120, s6, v143
	v_lshrrev_b32_e32 v142, 4, v119
	v_lshlrev_b32_e32 v110, 3, v142
	v_or_b32_e32 v141, 16, v143
	v_or_b32_e32 v118, s6, v141
	s_ashr_i32 s1, s0, 31
	v_lshl_or_b32 v83, v83, 6, v119
	v_mul_u32_u24_e32 v83, 0x90, v83
	v_lshlrev_b32_e32 v84, 6, v84
	v_add3_u32 v83, 0, v83, v84
	v_mov_b32_e32 v150, 0
	v_mov_b32_e32 v153, 0
	s_waitcnt vmcnt(33)
	ds_write_b128 v10, v[2:5]
	v_mul_lo_u32 v2, v12, s43
	v_add3_u32 v2, v13, v2, v11
	s_waitcnt vmcnt(32)
	ds_write_b128 v2, v[6:9]
	v_and_b32_e32 v2, 48, v119
	v_mov_b32_e32 v3, v111
	v_lshl_add_u64 v[4:5], s[28:29], 0, v[2:3]
	v_lshl_add_u64 v[6:7], v[4:5], 0, s[8:9]
	v_lshlrev_b32_e32 v8, 7, v140
	v_mov_b32_e32 v9, v111
	v_lshl_add_u64 v[10:11], v[6:7], 0, v[8:9]
	s_waitcnt vmcnt(31)
	s_waitcnt vmcnt(30)
	s_waitcnt vmcnt(29)
	s_waitcnt vmcnt(28)
	s_waitcnt vmcnt(27)
	s_waitcnt vmcnt(26)
	s_waitcnt vmcnt(25)
	s_waitcnt vmcnt(24)
	s_waitcnt vmcnt(23)
	s_waitcnt vmcnt(22)
	s_waitcnt vmcnt(21)
	s_waitcnt vmcnt(20)
	s_waitcnt vmcnt(19)
	s_waitcnt vmcnt(18)
	s_waitcnt vmcnt(17)
	s_waitcnt vmcnt(16)
	s_waitcnt vmcnt(15)
	s_waitcnt vmcnt(14)
	s_waitcnt vmcnt(13)
	s_waitcnt vmcnt(12)
	s_waitcnt vmcnt(11)
	s_waitcnt vmcnt(10)
	s_waitcnt vmcnt(9)
	s_waitcnt vmcnt(8)
	s_waitcnt vmcnt(7)
	s_waitcnt vmcnt(6)
	s_waitcnt vmcnt(5)
	s_waitcnt vmcnt(4)
	s_waitcnt vmcnt(3)
	s_waitcnt vmcnt(2)
	s_waitcnt vmcnt(1)
	s_waitcnt vmcnt(0)
	global_load_dwordx4 v[70:73], v[10:11], off
	global_load_dwordx4 v[46:49], v[10:11], off offset:64
	global_load_dwordx4 v[62:65], v[10:11], off offset:2048
	global_load_dwordx4 v[30:33], v[10:11], off offset:2112
	v_or_b32_e32 v10, 0x1000, v8
	v_mov_b32_e32 v11, v111
	v_lshl_add_u64 v[12:13], v[6:7], 0, v[10:11]
	global_load_dwordx4 v[54:57], v[12:13], off
	global_load_dwordx4 v[22:25], v[12:13], off offset:64
	v_or_b32_e32 v12, 0x1800, v8
	v_mov_b32_e32 v13, v111
	v_lshl_add_u64 v[6:7], v[6:7], 0, v[12:13]
	v_lshl_add_u64 v[4:5], v[4:5], 0, s[4:5]
	global_load_dwordx4 v[50:53], v[6:7], off
	global_load_dwordx4 v[18:21], v[6:7], off offset:64
	v_lshl_add_u64 v[6:7], v[4:5], 0, v[8:9]
	global_load_dwordx4 v[78:81], v[6:7], off
	global_load_dwordx4 v[42:45], v[6:7], off offset:64
	global_load_dwordx4 v[74:77], v[6:7], off offset:2048
	global_load_dwordx4 v[38:41], v[6:7], off offset:2112
	v_lshl_add_u64 v[6:7], v[4:5], 0, v[10:11]
	v_lshl_add_u64 v[4:5], v[4:5], 0, v[12:13]
	s_lshl_b32 s4, s0, 6
	global_load_dwordx4 v[66:69], v[6:7], off
	global_load_dwordx4 v[34:37], v[6:7], off offset:64
	global_load_dwordx4 v[58:61], v[4:5], off
	global_load_dwordx4 v[26:29], v[4:5], off offset:64
	s_ashr_i32 s5, s4, 31
	v_mad_u64_u32 v[4:5], s[8:9], v120, s57, v[114:115]
	v_mad_i32_i24 v5, s7, v117, v5
	s_lshl_b64 s[4:5], s[4:5], 1
	v_lshl_add_u64 v[4:5], v[4:5], 0, s[4:5]
	v_lshl_add_u64 v[4:5], v[4:5], 0, v[110:111]
	global_load_dwordx2 v[138:139], v[4:5], off offset:3072
	global_load_dwordx2 v[136:137], v[4:5], off offset:3104
	global_load_dwordx2 v[134:135], v[4:5], off offset:3136
	global_load_dwordx2 v[132:133], v[4:5], off offset:3168
	v_mad_u64_u32 v[4:5], s[8:9], v118, s57, v[114:115]
	s_lshl_b64 s[0:1], s[0:1], 2
	v_mad_i32_i24 v5, s7, v117, v5
	s_add_u32 s0, s48, s0
	v_lshl_add_u64 v[4:5], v[4:5], 0, s[4:5]
	s_addc_u32 s1, s49, s1
	s_lshl_b32 s36, s13, 6
	v_lshl_add_u64 v[4:5], v[4:5], 0, v[110:111]
	s_ashr_i32 s37, s36, 31
	global_load_dwordx2 v[130:131], v[4:5], off offset:3072
	global_load_dwordx2 v[128:129], v[4:5], off offset:3104
	global_load_dwordx2 v[126:127], v[4:5], off offset:3136
	global_load_dwordx2 v[124:125], v[4:5], off offset:3168
	global_load_dword v122, v111, s[0:1]
	s_lshl_b64 s[0:1], s[36:37], 2
	s_add_u32 s0, s40, s0
	s_addc_u32 s1, s41, s1
	global_load_dwordx4 v[14:17], v2, s[0:1]
	global_load_dwordx4 v[10:13], v2, s[0:1] offset:64
	global_load_dwordx4 v[6:9], v2, s[0:1] offset:128
	s_nop 0
	global_load_dwordx4 v[2:5], v2, s[0:1] offset:192
	v_lshl_or_b32 v84, v86, 16, v85
	v_lshl_or_b32 v85, v88, 16, v87
	v_lshl_or_b32 v86, v90, 16, v89
	v_lshl_or_b32 v87, v92, 16, v91
	ds_write_b128 v83, v[84:87] offset:27648
	v_lshl_or_b32 v84, v94, 16, v93
	v_lshl_or_b32 v85, v96, 16, v95
	v_lshl_or_b32 v86, v98, 16, v97
	v_lshl_or_b32 v87, v100, 16, v99
	ds_write_b128 v83, v[84:87] offset:27664
	v_lshl_or_b32 v84, v102, 16, v101
	v_lshl_or_b32 v85, v104, 16, v103
	v_lshl_or_b32 v86, v106, 16, v105
	v_lshl_or_b32 v87, v108, 16, v107
	ds_write_b128 v83, v[84:87] offset:27680
	v_lshl_or_b32 v84, v121, 16, v109
	v_lshl_or_b32 v85, v145, 16, v144
	v_lshl_or_b32 v86, v147, 16, v146
	v_lshl_or_b32 v87, v149, 16, v148
	v_and_b32_e32 v144, 48, v82
	v_mul_u32_u24_e32 v145, 0x90, v143
	ds_write_b128 v83, v[84:87] offset:27696
	v_add3_u32 v86, 0, v145, v144
	s_waitcnt lgkmcnt(0)
	s_barrier
	ds_read_b128 v[90:93], v86 offset:9216
	v_lshl_or_b32 v146, s13, 4, v140
	v_mul_lo_u32 v148, v146, s43
	v_add3_u32 v87, 0, v148, v144
	ds_read_b128 v[82:85], v87
	ds_read_b128 v[94:97], v86 offset:9280
	ds_read_b128 v[86:89], v87 offset:64
	s_waitcnt lgkmcnt(2)
	v_mfma_f32_16x16x32_bf16 v[90:93], v[90:93], v[82:85], 0
	v_lshlrev_b32_e32 v110, 2, v142
	v_or_b32_e32 v155, s3, v110
	s_add_i32 s3, 0, 0x18c00
	s_waitcnt lgkmcnt(0)
	v_mfma_f32_16x16x32_bf16 v[90:93], v[94:97], v[86:89], v[90:93]
	v_lshlrev_b32_e32 v94, 2, v155
	v_add_u32_e32 v95, 0, v94
	v_add_u32_e32 v158, s3, v94
	v_add_u32_e32 v156, 0x19400, v95
	v_lshlrev_b32_e32 v95, 2, v146
	v_add_u32_e32 v94, s58, v94
	v_add_u32_e32 v147, s3, v95
	v_add_u32_e32 v149, s58, v95
	ds_read_b128 v[94:97], v94
	ds_read_b128 v[106:109], v158
	ds_read_b128 v[102:105], v156
	ds_read_b32 v151, v147
	ds_read_b32 v152, v149
	ds_read_b128 v[98:101], v156 offset:1024
	s_lshl_b32 s26, s12, 1
	s_cmp_le_i32 s26, s13
	v_mov_b32_e32 v121, s7
	s_cselect_b64 s[0:1], -1, 0
	s_cmp_gt_i32 s26, s13
	v_cmp_le_i32_e32 vcc, v155, v146
	s_cbranch_scc1 .LBB0_829
	s_waitcnt lgkmcnt(2)
	v_sub_f32_e32 v106, v151, v106
	v_min_f32_e32 v106, 0, v106
	v_mul_f32_e32 v106, 0x3fb8aa3b, v106
	v_exp_f32_e32 v106, v106
	s_nop 0
	v_mul_f32_e32 v102, v102, v106
	v_cndmask_b32_e32 v153, 0, v102, vcc
